# r42 + gdn_pre f32-MFMA blocks (kk mask loop unrolled, chunk-output block) double-buffered LDS reads; first epilogue read batch issued before last MFMA group
# speedup vs baseline: 1.0082x; 1.0002x over previous
.LBB0_327:
	ds_read_b128 v[150:153], v59
	ds_read_b128 v[154:157], v148
	ds_read_b128 v[230:233], v59 offset:32
	ds_read_b128 v[234:237], v148 offset:32
	s_waitcnt lgkmcnt(2)
	v_mfma_f32_32x32x2_f32 v[2:17], v150, v154, v[2:17]
	v_mfma_f32_32x32x2_f32 v[2:17], v151, v155, v[2:17]
	v_mfma_f32_32x32x2_f32 v[2:17], v152, v156, v[2:17]
	v_mfma_f32_32x32x2_f32 v[2:17], v153, v157, v[2:17]
	ds_read_b128 v[150:153], v59 offset:64
	ds_read_b128 v[154:157], v148 offset:64
	s_waitcnt lgkmcnt(2)
	v_mfma_f32_32x32x2_f32 v[2:17], v230, v234, v[2:17]
	v_mfma_f32_32x32x2_f32 v[2:17], v231, v235, v[2:17]
	v_mfma_f32_32x32x2_f32 v[2:17], v232, v236, v[2:17]
	v_mfma_f32_32x32x2_f32 v[2:17], v233, v237, v[2:17]
	ds_read_b128 v[230:233], v59 offset:96
	ds_read_b128 v[234:237], v148 offset:96
	s_waitcnt lgkmcnt(2)
	v_mfma_f32_32x32x2_f32 v[2:17], v150, v154, v[2:17]
	v_mfma_f32_32x32x2_f32 v[2:17], v151, v155, v[2:17]
	v_mfma_f32_32x32x2_f32 v[2:17], v152, v156, v[2:17]
	v_mfma_f32_32x32x2_f32 v[2:17], v153, v157, v[2:17]
	ds_read_b128 v[150:153], v59 offset:128
	ds_read_b128 v[154:157], v148 offset:128
	s_waitcnt lgkmcnt(2)
	v_mfma_f32_32x32x2_f32 v[2:17], v230, v234, v[2:17]
	v_mfma_f32_32x32x2_f32 v[2:17], v231, v235, v[2:17]
	v_mfma_f32_32x32x2_f32 v[2:17], v232, v236, v[2:17]
	v_mfma_f32_32x32x2_f32 v[2:17], v233, v237, v[2:17]
	ds_read_b128 v[230:233], v59 offset:160
	ds_read_b128 v[234:237], v148 offset:160
	s_waitcnt lgkmcnt(2)
	v_mfma_f32_32x32x2_f32 v[2:17], v150, v154, v[2:17]
	v_mfma_f32_32x32x2_f32 v[2:17], v151, v155, v[2:17]
	v_mfma_f32_32x32x2_f32 v[2:17], v152, v156, v[2:17]
	v_mfma_f32_32x32x2_f32 v[2:17], v153, v157, v[2:17]
	ds_read_b128 v[150:153], v59 offset:192
	ds_read_b128 v[154:157], v148 offset:192
	s_waitcnt lgkmcnt(2)
	v_mfma_f32_32x32x2_f32 v[2:17], v230, v234, v[2:17]
	v_mfma_f32_32x32x2_f32 v[2:17], v231, v235, v[2:17]
	v_mfma_f32_32x32x2_f32 v[2:17], v232, v236, v[2:17]
	v_mfma_f32_32x32x2_f32 v[2:17], v233, v237, v[2:17]
	ds_read_b128 v[230:233], v59 offset:224
	ds_read_b128 v[234:237], v148 offset:224
	s_waitcnt lgkmcnt(2)
	v_mfma_f32_32x32x2_f32 v[2:17], v150, v154, v[2:17]
	v_mfma_f32_32x32x2_f32 v[2:17], v151, v155, v[2:17]
	v_mfma_f32_32x32x2_f32 v[2:17], v152, v156, v[2:17]
	v_mfma_f32_32x32x2_f32 v[2:17], v153, v157, v[2:17]
	s_waitcnt lgkmcnt(0)
	ds_read_b32 v59, v70
	ds_read_b32 v197, v85
	ds_read_b32 v198, v86
	ds_read_b32 v199, v87
	ds_read_b32 v200, v88
	ds_read_b32 v201, v89
	ds_read_b32 v202, v90
	ds_read_b32 v203, v91
	ds_read_b32 v204, v108
	ds_read_b32 v205, v109
	ds_read_b32 v206, v110
	ds_read_b32 v207, v111
	ds_read_b32 v208, v112
	v_mfma_f32_32x32x2_f32 v[2:17], v230, v234, v[2:17]
	v_mfma_f32_32x32x2_f32 v[2:17], v231, v235, v[2:17]
	v_mfma_f32_32x32x2_f32 v[2:17], v232, v236, v[2:17]
	v_mfma_f32_32x32x2_f32 v[2:17], v233, v237, v[2:17]
	s_waitcnt lgkmcnt(0)
	ds_read_b32 v209, v113
	ds_read_b32 v210, v114
	ds_read_b32 v211, v115
	ds_read_b32 v212, v116
	ds_read_b32 v213, v117
	ds_read_b32 v214, v118
	ds_read_b32 v215, v119
	ds_read_b32 v216, v120
	ds_read_b32 v217, v121
	ds_read_b32 v218, v122
	ds_read_b32 v219, v123
	ds_read_b32 v220, v124
	s_waitcnt lgkmcnt(0)
	ds_read_b32 v221, v125
	ds_read_b32 v222, v126
	ds_read_b32 v223, v127
	ds_read_b32 v224, v128
	ds_read_b32 v225, v129
	ds_read_b32 v226, v130
	ds_read_b32 v227, v131
	ds_read_b32 v228, v132
	s_waitcnt lgkmcnt(0)
	v_mov_b32_e32 v148, 0
	s_and_saveexec_b64 s[38:39], s[34:35]
	s_cbranch_execz .LBB0_330
	v_mov_b32_e32 v148, v197
	v_sub_f32_e32 v148, v148, v59
	v_mul_f32_e32 v148, 0x3fb8aa3b, v148
	v_exp_f32_e32 v148, v148

.LBB0_475:
	ds_read_b128 v[148:151], v76
	ds_read2_b32 v[152:153], v136 offset1:132
	v_add_u32_e32 v59, 0x400, v136
	ds_read2_b32 v[244:245], v59 offset0:8 offset1:140
	ds_read_b128 v[238:241], v76 offset:32
	v_add_u32_e32 v59, 0x1000, v136
	ds_read2_b32 v[242:243], v59 offset0:32 offset1:164
	v_add_u32_e32 v59, 0x1400, v136
	ds_read2_b32 v[246:247], v59 offset0:40 offset1:172
	s_waitcnt lgkmcnt(4)
	v_mfma_f32_32x32x2_f32 v[2:17], v148, v152, 0
	v_mfma_f32_32x32x2_f32 v[2:17], v149, v153, v[2:17]
	s_waitcnt lgkmcnt(3)
	v_mfma_f32_32x32x2_f32 v[2:17], v150, v244, v[2:17]
	v_mfma_f32_32x32x2_f32 v[2:17], v151, v245, v[2:17]
	ds_read_b128 v[148:151], v76 offset:64
	v_add_u32_e32 v59, 0x2000, v136
	ds_read2_b32 v[152:153], v59 offset0:64 offset1:196
	v_add_u32_e32 v59, 0x2400, v136
	ds_read2_b32 v[244:245], v59 offset0:72 offset1:204
	s_waitcnt lgkmcnt(4)
	v_mfma_f32_32x32x2_f32 v[2:17], v238, v242, v[2:17]
	v_mfma_f32_32x32x2_f32 v[2:17], v239, v243, v[2:17]
	s_waitcnt lgkmcnt(3)
	v_mfma_f32_32x32x2_f32 v[2:17], v240, v246, v[2:17]
	v_mfma_f32_32x32x2_f32 v[2:17], v241, v247, v[2:17]
	ds_read_b128 v[238:241], v76 offset:96
	v_add_u32_e32 v59, 0x3000, v136
	ds_read2_b32 v[242:243], v59 offset0:96 offset1:228
	v_add_u32_e32 v59, 0x3400, v136
	ds_read2_b32 v[246:247], v59 offset0:104 offset1:236
	s_waitcnt lgkmcnt(4)
	v_mfma_f32_32x32x2_f32 v[2:17], v148, v152, v[2:17]
	v_mfma_f32_32x32x2_f32 v[2:17], v149, v153, v[2:17]
	s_waitcnt lgkmcnt(3)
	v_mfma_f32_32x32x2_f32 v[2:17], v150, v244, v[2:17]
	v_mfma_f32_32x32x2_f32 v[2:17], v151, v245, v[2:17]
	s_waitcnt lgkmcnt(1)
	v_mfma_f32_32x32x2_f32 v[2:17], v238, v242, v[2:17]
	v_mfma_f32_32x32x2_f32 v[2:17], v239, v243, v[2:17]
	s_waitcnt lgkmcnt(0)
	v_mfma_f32_32x32x2_f32 v[2:17], v240, v246, v[2:17]
	v_mfma_f32_32x32x2_f32 v[2:17], v241, v247, v[2:17]
	s_and_saveexec_b64 s[2:3], s[24:25]
	s_cbranch_execz .LBB0_293
	ds_read_b128 v[148:151], v76 offset:128
	v_add_u32_e32 v59, 0x4200, v136
	ds_read2_b32 v[152:153], v59 offset1:132
	v_add_u32_e32 v59, 0x4600, v136
	ds_read2_b32 v[244:245], v59 offset0:8 offset1:140
	ds_read_b128 v[238:241], v76 offset:160
	v_add_u32_e32 v59, 0x5200, v136
	ds_read2_b32 v[242:243], v59 offset0:32 offset1:164
	v_add_u32_e32 v59, 0x5600, v136
	ds_read2_b32 v[246:247], v59 offset0:40 offset1:172
	s_waitcnt lgkmcnt(4)
	v_mfma_f32_32x32x2_f32 v[2:17], v148, v152, v[2:17]
	v_mfma_f32_32x32x2_f32 v[2:17], v149, v153, v[2:17]
	s_waitcnt lgkmcnt(3)
	v_mfma_f32_32x32x2_f32 v[2:17], v150, v244, v[2:17]
	v_mfma_f32_32x32x2_f32 v[2:17], v151, v245, v[2:17]
	ds_read_b128 v[148:151], v76 offset:192
	v_add_u32_e32 v59, 0x6200, v136
	ds_read2_b32 v[152:153], v59 offset0:64 offset1:196
	v_add_u32_e32 v59, 0x6600, v136
	ds_read2_b32 v[244:245], v59 offset0:72 offset1:204
	s_waitcnt lgkmcnt(4)
	v_mfma_f32_32x32x2_f32 v[2:17], v238, v242, v[2:17]
	v_mfma_f32_32x32x2_f32 v[2:17], v239, v243, v[2:17]
	s_waitcnt lgkmcnt(3)
	v_mfma_f32_32x32x2_f32 v[2:17], v240, v246, v[2:17]
	v_mfma_f32_32x32x2_f32 v[2:17], v241, v247, v[2:17]
	ds_read_b128 v[238:241], v76 offset:224
	v_add_u32_e32 v59, 0x7200, v136
	ds_read2_b32 v[242:243], v59 offset0:96 offset1:228
	v_add_u32_e32 v59, 0x7600, v136
	ds_read2_b32 v[246:247], v59 offset0:104 offset1:236
	s_waitcnt lgkmcnt(4)
	v_mfma_f32_32x32x2_f32 v[2:17], v148, v152, v[2:17]
	v_mfma_f32_32x32x2_f32 v[2:17], v149, v153, v[2:17]
	s_waitcnt lgkmcnt(3)
	v_mfma_f32_32x32x2_f32 v[2:17], v150, v244, v[2:17]
	v_mfma_f32_32x32x2_f32 v[2:17], v151, v245, v[2:17]
	s_waitcnt lgkmcnt(1)
	v_mfma_f32_32x32x2_f32 v[2:17], v238, v242, v[2:17]
	v_mfma_f32_32x32x2_f32 v[2:17], v239, v243, v[2:17]
	s_waitcnt lgkmcnt(0)
	v_mfma_f32_32x32x2_f32 v[2:17], v240, v246, v[2:17]
	v_mfma_f32_32x32x2_f32 v[2:17], v241, v247, v[2:17]
	s_branch .LBB0_293
